# scan step: the 8 masked decay-mask LDS reads issued together before the masked blocks (was 8 serialized LDS round trips)
# speedup vs baseline: 1.0160x; 1.0040x over previous
.LBB0_1482:
	s_or_b64 exec, exec, s[2:3]
	s_bitcmp0_b32 s64, 0
	s_waitcnt lgkmcnt(0)
	v_mfma_f32_16x16x32_bf16 v[52:55], v[52:55], v[56:59], 0
	s_cselect_b64 s[0:1], -1, 0
	s_and_b64 s[2:3], s[0:1], exec
	s_mov_b32 s2, 0x23100
	v_mfma_f32_16x16x32_bf16 v[60:63], v[60:63], v[56:59], 0
	s_cselect_b32 s3, 0x8800, s2
	s_cselect_b32 s2, s89, 0x27900
	s_add_i32 s64, s77, s2
	v_mfma_f32_16x16x32_bf16 v[64:67], v[64:67], v[56:59], 0
	v_mfma_f32_16x16x32_bf16 v[56:59], v[68:71], v[56:59], 0
	ds_read_b128 v[68:71], v173 offset:64
	ds_read_b128 v[76:79], v132 offset:64
	s_waitcnt lgkmcnt(0)
	v_mfma_f32_16x16x32_bf16 v[60:63], v[72:75], v[68:71], v[60:63]
	ds_read_b128 v[72:75], v175 offset:17472
	v_mfma_f32_16x16x32_bf16 v[52:55], v[76:79], v[68:71], v[52:55]
	ds_read_b128 v[76:79], v133 offset:64
	s_waitcnt lgkmcnt(0)
	v_mfma_f32_16x16x32_bf16 v[64:67], v[72:75], v[68:71], v[64:67]
	ds_read_b128 v[72:75], v174 offset:17536
	ds_read_b128 v[80:83], v173 offset:128
	v_mfma_f32_16x16x32_bf16 v[56:59], v[76:79], v[68:71], v[56:59]
	ds_read_b128 v[68:71], v132 offset:128
	s_waitcnt lgkmcnt(0)
	v_mfma_f32_16x16x32_bf16 v[60:63], v[72:75], v[80:83], v[60:63]
	ds_read_b128 v[72:75], v175 offset:17536
	v_mfma_f32_16x16x32_bf16 v[52:55], v[68:71], v[80:83], v[52:55]
	ds_read_b128 v[68:71], v133 offset:128
	s_waitcnt lgkmcnt(0)
	v_mfma_f32_16x16x32_bf16 v[72:75], v[72:75], v[80:83], v[64:67]
	s_nop 2
	ds_read_b128 v[64:67], v174 offset:17600
	ds_read_b128 v[76:79], v173 offset:192
	v_mfma_f32_16x16x32_bf16 v[56:59], v[68:71], v[80:83], v[56:59]
	ds_read_b128 v[68:71], v132 offset:192
	ds_read_b128 v[80:83], v175 offset:17600
	ds_read_b128 v[84:87], v133 offset:192
	s_waitcnt lgkmcnt(0)
	v_mfma_f32_16x16x32_bf16 v[52:55], v[68:71], v[76:79], v[52:55]
	v_mov_b32_e32 v68, s64
	ds_read_b32 v194, v68
	v_mfma_f32_16x16x32_bf16 v[64:67], v[64:67], v[76:79], v[60:63]
	v_mfma_f32_16x16x32_bf16 v[60:63], v[80:83], v[76:79], v[72:75]
	v_mfma_f32_16x16x32_bf16 v[56:59], v[84:87], v[76:79], v[56:59]
	v_add_u32_e32 v193, s3, v172
	ds_read_b128 v[68:71], v193
	v_add_u32_e32 v190, v110, v160
	ds_read_b128 v[72:75], v193 offset:2304
	ds_read_b128 v[76:79], v190 offset:62464
	ds_read_b128 v[80:83], v193 offset:4608
	ds_read_b128 v[84:87], v193 offset:6912
	v_add_u32_e32 v192, v168, v160
	s_waitcnt lgkmcnt(0)
	v_mfma_f32_16x16x32_bf16 v[72:75], v[72:75], v[76:79], 0
	v_add_u32_e32 v188, v169, v160
	v_add_u32_e32 v195, s2, v96
	s_add_i32 s64, s2, 0
	v_mfma_f32_16x16x32_bf16 v[88:91], v[80:83], v[76:79], 0
	ds_read_b128 v[80:83], v159
	v_mfma_f32_16x16x32_bf16 v[68:71], v[68:71], v[76:79], 0
	v_mfma_f32_16x16x32_bf16 v[196:199], v[84:87], v[76:79], 0
	ds_read_b128 v[76:79], v192 offset:53248
	ds_read_b128 v[84:87], v188 offset:53248
	s_waitcnt lgkmcnt(0)
	v_mfma_f32_16x16x32_bf16 v[200:203], v[80:83], v[76:79], 0
	ds_read_b128 v[76:79], v193 offset:64
	ds_read_b128 v[222:225], v190 offset:62528
	v_mfma_f32_16x16x32_bf16 v[226:229], v[80:83], v[84:87], 0
	ds_read_b128 v[80:83], v193 offset:2368
	s_waitcnt lgkmcnt(0)
	v_mfma_f32_16x16x32_bf16 v[76:79], v[76:79], v[222:225], v[68:71]
	s_nop 2
	ds_read_b128 v[68:71], v193 offset:4672
	s_waitcnt lgkmcnt(0)
	v_mfma_f32_16x16x32_bf16 v[84:87], v[68:71], v[222:225], v[88:91]
	ds_read_b128 v[68:71], v159 offset:64
	v_mfma_f32_16x16x32_bf16 v[80:83], v[80:83], v[222:225], v[72:75]
	s_nop 2
	ds_read_b128 v[72:75], v193 offset:6976
	s_waitcnt lgkmcnt(0)
	v_mfma_f32_16x16x32_bf16 v[88:91], v[72:75], v[222:225], v[196:199]
	ds_read_b128 v[72:75], v192 offset:53312
	ds_read_b128 v[222:225], v188 offset:53312
	s_nop 0
	ds_read_b32 v196, v195
	v_add_u32_e32 v232, s64, v143
	v_add_u32_e32 v233, s64, v142
	v_add_u32_e32 v234, s64, v141
	v_add_u32_e32 v235, s64, v140
	v_add_u32_e32 v236, s64, v139
	v_add_u32_e32 v237, s64, v138
	v_add_u32_e32 v238, s64, v136
	v_add_u32_e32 v239, s64, v135
	ds_read_b32 v232, v232
	ds_read_b32 v233, v233
	ds_read_b32 v234, v234
	ds_read_b32 v235, v235
	ds_read_b32 v236, v236
	ds_read_b32 v237, v237
	ds_read_b32 v238, v238
	ds_read_b32 v239, v239
	v_mov_b32_e32 v197, 0
	s_waitcnt lgkmcnt(0)
	v_mfma_f32_16x16x32_bf16 v[72:75], v[68:71], v[72:75], v[200:203]
	v_mov_b32_e32 v198, 0
	v_mfma_f32_16x16x32_bf16 v[68:71], v[68:71], v[222:225], v[226:229]
	s_and_saveexec_b64 s[2:3], s[58:59]
	s_cbranch_execz .LBB0_1496
	v_sub_f32_e32 v180, v196, v232
	v_mul_f32_e32 v180, 0x3fb8aa3b, v180
	v_exp_f32_e32 v180, v180
	s_nop 0
	v_mul_f32_e32 v198, v64, v180
	s_or_b64 exec, exec, s[2:3]
	v_mov_b32_e32 v199, 0
	s_and_saveexec_b64 s[2:3], s[56:57]
	s_cbranch_execnz .LBB0_1497

.LBB0_1485:
	v_sub_f32_e32 v64, v196, v234
	v_mul_f32_e32 v64, 0x3fb8aa3b, v64
	v_exp_f32_e32 v64, v64
	s_nop 0
	v_mul_f32_e32 v197, v66, v64
.LBB0_1486:
	s_or_b64 exec, exec, s[2:3]
	v_mov_b32_e32 v64, 0
	v_mov_b32_e32 v65, 0
	s_and_saveexec_b64 s[2:3], s[52:53]
	s_cbranch_execz .LBB0_1488
	v_sub_f32_e32 v65, v196, v235
	v_mul_f32_e32 v65, 0x3fb8aa3b, v65
	v_exp_f32_e32 v65, v65
	s_nop 0
	v_mul_f32_e32 v65, v67, v65
.LBB0_1488:
	s_or_b64 exec, exec, s[2:3]
	v_cvt_pk_bf16_f32 v66, v198, v199
	v_cvt_pk_bf16_f32 v67, v197, v65
	ds_write_b64 v144, v[66:67]
	s_and_saveexec_b64 s[2:3], s[50:51]
	s_cbranch_execz .LBB0_1490
	v_sub_f32_e32 v64, v196, v236
	v_mul_f32_e32 v64, 0x3fb8aa3b, v64
	v_exp_f32_e32 v64, v64
	s_nop 0
	v_mul_f32_e32 v64, v60, v64
.LBB0_1490:
	s_or_b64 exec, exec, s[2:3]
	v_mov_b32_e32 v60, 0
	v_mov_b32_e32 v65, 0
	s_and_saveexec_b64 s[2:3], s[48:49]
	s_cbranch_execz .LBB0_1498
	v_sub_f32_e32 v65, v196, v237
	v_mul_f32_e32 v65, 0x3fb8aa3b, v65
	v_exp_f32_e32 v65, v65
	s_nop 0
	v_mul_f32_e32 v65, v61, v65
	s_or_b64 exec, exec, s[2:3]
	s_and_saveexec_b64 s[2:3], s[46:47]
	s_cbranch_execnz .LBB0_1499

.LBB0_1493:
	v_sub_f32_e32 v61, v196, v239
	v_mul_f32_e32 v61, 0x3fb8aa3b, v61
	v_exp_f32_e32 v61, v61
	s_nop 0
	v_mul_f32_e32 v61, v63, v61

.LBB0_1497:
	v_sub_f32_e32 v64, v196, v233
	v_mul_f32_e32 v64, 0x3fb8aa3b, v64
	v_exp_f32_e32 v64, v64
	s_nop 0
	v_mul_f32_e32 v199, v65, v64
	s_or_b64 exec, exec, s[2:3]
	s_and_saveexec_b64 s[2:3], s[54:55]
	s_cbranch_execnz .LBB0_1485
	s_branch .LBB0_1486

.LBB0_1499:
	v_sub_f32_e32 v60, v196, v238
	v_mul_f32_e32 v60, 0x3fb8aa3b, v60
	v_exp_f32_e32 v60, v60
	s_nop 0
	v_mul_f32_e32 v60, v62, v60
	s_or_b64 exec, exec, s[2:3]
	v_mov_b32_e32 v61, 0
	s_and_saveexec_b64 s[2:3], s[44:45]
	s_cbranch_execnz .LBB0_1493
	s_branch .LBB0_1494
